# v019: skinny-GEMM wave-0 reduce issues all 8 LDS partial reads up front with counted lgkmcnt waits (P1/P4a/P4b/P5/P8), same summation order
# baseline (speedup 1.0000x reference)
; __device__ __forceinline__ float sigmoid_f(float x) { return __builtin_amdgcn_rcpf(1.f + __builtin_amdgcn_exp2f(-1.4426950408889634f * x)); }
;     __device__ __forceinline__ void apply(int row, int tile, int g, f32x4 v, f32x4) const { *(u32x2*)(O + (size_t)row * D + 16 * tile + 4 * g) = pack4(v); }
; template <class SE> __device__ __forceinline__ void skinny_gemm(const Frame& F, const bf16* Am, const bf16* Bt, int ntiles, int K, const SE& E) {
;     ...
;         part[w * 64 + F.lane] = acc0; if (SE::DUAL) part[512 + w * 64 + F.lane] = acc1;
;         asm volatile("s_waitcnt lgkmcnt(0)" ::: "memory"); __builtin_amdgcn_s_barrier(); asm volatile("" ::: "memory");
;         if (w == 0) {
;             f32x4 t0 = part[F.lane], t1 = {0.f, 0.f, 0.f, 0.f}; if (SE::DUAL) t1 = part[512 + F.lane];
; #pragma unroll
;             for (int ww = 1; ww < 8; ++ww) { t0 += part[ww * 64 + F.lane]; if (SE::DUAL) t1 += part[512 + ww * 64 + F.lane]; }
;             E.apply(MF + j, tile, g, t0, t1);
;     __device__ __forceinline__ void apply(int row, int tile, int g, f32x4 v, f32x4) const {
;         const int c = 16 * tile + 4 * g, pn = c >> 8, cl = c & 255;
;         bf16* base; int ld, col, act;
;         if (pn < 4) { base = RQ; ld = 1024; col = pn * 256 + cl; act = 0; }
;         else if (pn < 8) { base = RK; ld = 1024; col = (pn - 4) * 256 + cl; act = 0; }
;         else if (pn < 16) { base = RV; ld = 2048; col = (pn - 8) * 256 + cl; act = 0; }
;         else if (pn < 24) { base = RG; ld = 2048; col = (pn - 16) * 256 + cl; act = 1; }
;         else if (pn < 28) { base = HQ; ld = 1024; col = (pn - 24) * 256 + cl; act = 1; }
;         else if (pn < 32) { col = (pn - 28) * 256 + cl; const f32x4 l4 = *(const f32x4*)(lb + col);
;             for (int i = 0; i < 4; ++i) v[i] = (1.f - l4[i]) * sigmoid_f(-v[i]);
;             *(f32x4*)(HK + (size_t)row * 1024 + col) = v; return; }
;         else if (pn < 40) { base = HI; ld = 2048; col = (pn - 32) * 256 + cl; act = 0; }
;         else if (pn < 48) { base = HG; ld = 2048; col = (pn - 40) * 256 + cl; act = 1; }
;         else if (pn < 56) { base = GR; ld = 2048; col = (pn - 48) * 256 + cl; act = 2; }
;         else { base = GH; ld = 2048; col = (pn - 56) * 256 + cl; act = 2; }
.LBB0_218:
	ds_write_b128 v83, v[64:67]
	s_waitcnt lgkmcnt(0)
	s_barrier
	s_and_b64 vcc, exec, s[24:25]
	s_cbranch_vccz .LBB0_181
	ds_read_b128 v[64:67], v84
	ds_read_b128 v[74:77], v84 offset:1024
	ds_read_b128 v[100:103], v84 offset:2048
	ds_read_b128 v[104:107], v84 offset:3072
	ds_read_b128 v[108:111], v84 offset:4096
	ds_read_b128 v[112:115], v84 offset:5120
	ds_read_b128 v[116:119], v84 offset:6144
	ds_read_b128 v[120:123], v84 offset:7168
	s_ashr_i32 s20, s66, 4
	s_cmp_lt_i32 s20, 4
	s_waitcnt lgkmcnt(6)
	v_pk_add_f32 v[76:77], v[66:67], v[76:77]
	v_pk_add_f32 v[74:75], v[64:65], v[74:75]
	s_waitcnt lgkmcnt(5)
	v_pk_add_f32 v[76:77], v[76:77], v[102:103]
	v_pk_add_f32 v[74:75], v[74:75], v[100:101]
	s_waitcnt lgkmcnt(4)
	v_pk_add_f32 v[76:77], v[76:77], v[106:107]
	v_pk_add_f32 v[74:75], v[74:75], v[104:105]
	s_waitcnt lgkmcnt(3)
	v_pk_add_f32 v[76:77], v[76:77], v[110:111]
	v_pk_add_f32 v[74:75], v[74:75], v[108:109]
	s_waitcnt lgkmcnt(2)
	v_pk_add_f32 v[76:77], v[76:77], v[114:115]
	v_pk_add_f32 v[74:75], v[74:75], v[112:113]
	s_waitcnt lgkmcnt(1)
	v_pk_add_f32 v[76:77], v[76:77], v[118:119]
	v_pk_add_f32 v[74:75], v[74:75], v[116:117]
	s_waitcnt lgkmcnt(0)
	v_pk_add_f32 v[66:67], v[76:77], v[122:123]
	v_pk_add_f32 v[64:65], v[74:75], v[120:121]
	v_or_b32_e32 v74, s18, v82
	s_cbranch_scc1 .LBB0_237
	s_cmp_gt_u32 s20, 7
	v_and_b32_e32 v75, 0xfc, v74
	s_cbranch_scc0 .LBB0_238
	s_cmp_gt_u32 s20, 15
	s_cbranch_scc0 .LBB0_239
	s_cmp_gt_u32 s20, 23
	s_cbranch_scc0 .LBB0_240
	s_cmp_gt_u32 s20, 27
	s_cbranch_scc0 .LBB0_241
	s_cmp_gt_u32 s20, 31
	s_cbranch_scc0 .LBB0_242
	s_and_b32 s19, s18, 0xffffff00
	s_cmp_gt_u32 s20, 39
	s_mov_b64 s[28:29], -1
	s_cbranch_scc0 .LBB0_234
	s_mov_b64 s[30:31], -1
	s_cmp_gt_u32 s20, 47
	s_mov_b64 s[34:35], -1
	s_cbranch_scc0 .LBB0_232
	s_cmp_gt_u32 s20, 55
	s_mov_b64 s[26:27], -1
	s_cbranch_scc0 .LBB0_229
	s_add_i32 s20, s19, 0xffffc800
	v_or_b32_e32 v74, s20, v75
	s_mov_b64 s[26:27], 0

; __device__ __forceinline__ float bflo(unsigned w) { return __uint_as_float(w << 16); }
; __device__ __forceinline__ float bfhi(unsigned w) { return __uint_as_float(w & 0xffff0000u); }
; __device__ __forceinline__ u32x2 pack4(const f32x4 v) { u32x2 w; w.x = cvt_pk_bf16(v.x, v.y); w.y = cvt_pk_bf16(v.z, v.w); return w; }
;     __device__ __forceinline__ void apply(int row, int tile, int g, f32x4 v, f32x4) const { *(u32x2*)(O + (size_t)row * D + 16 * tile + 4 * g) = pack4(v); }
; template <class SE> __device__ __forceinline__ void skinny_gemm(const Frame& F, const bf16* Am, const bf16* Bt, int ntiles, int K, const SE& E) {
;     ...
;         part[w * 64 + F.lane] = acc0; if (SE::DUAL) part[512 + w * 64 + F.lane] = acc1;
;         asm volatile("s_waitcnt lgkmcnt(0)" ::: "memory"); __builtin_amdgcn_s_barrier(); asm volatile("" ::: "memory");
;         if (w == 0) {
;             f32x4 t0 = part[F.lane], t1 = {0.f, 0.f, 0.f, 0.f}; if (SE::DUAL) t1 = part[512 + F.lane];
; #pragma unroll
;             for (int ww = 1; ww < 8; ++ww) { t0 += part[ww * 64 + F.lane]; if (SE::DUAL) t1 += part[512 + ww * 64 + F.lane]; }
;             E.apply(MF + j, tile, g, t0, t1);
;     __device__ __forceinline__ void apply(int row, int tile, int g, f32x4 v, f32x4) const {
;         const size_t off = (size_t)row * D + 16 * tile + 4 * g; const u32x2 gg = *(const u32x2*)(G + off);
;         f32x4 o = {bflo(gg.x) * v.x, bfhi(gg.x) * v.y, bflo(gg.y) * v.z, bfhi(gg.y) * v.w};
;         if (ADD) { const u32x2 t = *(const u32x2*)(T + off); o.x += bflo(t.x); o.y += bfhi(t.x); o.z += bflo(t.y); o.w += bfhi(t.y); }
;         *(u32x2*)(O + off) = pack4(o);
.LBB0_613:
	ds_write_b128 v76, v[64:67]
	s_waitcnt lgkmcnt(0)
	s_barrier
	s_and_b64 vcc, exec, s[10:11]
	s_cbranch_vccz .LBB0_576
	ds_read_b128 v[64:67], v151
	ds_read_b128 v[78:81], v151 offset:1024
	ds_read_b128 v[100:103], v151 offset:2048
	ds_read_b128 v[104:107], v151 offset:3072
	ds_read_b128 v[108:111], v151 offset:4096
	ds_read_b128 v[112:115], v151 offset:5120
	ds_read_b128 v[116:119], v151 offset:6144
	ds_read_b128 v[120:123], v151 offset:7168
	s_ashr_i32 s15, s14, 31
	s_waitcnt lgkmcnt(6)
	v_pk_add_f32 v[74:75], v[66:67], v[80:81]
	v_pk_add_f32 v[78:79], v[64:65], v[78:79]
	s_waitcnt lgkmcnt(5)
	v_pk_add_f32 v[74:75], v[74:75], v[102:103]
	v_pk_add_f32 v[78:79], v[78:79], v[100:101]
	s_waitcnt lgkmcnt(4)
	v_pk_add_f32 v[74:75], v[74:75], v[106:107]
	v_pk_add_f32 v[78:79], v[78:79], v[104:105]
	s_waitcnt lgkmcnt(3)
	v_pk_add_f32 v[74:75], v[74:75], v[110:111]
	v_pk_add_f32 v[78:79], v[78:79], v[108:109]
	s_waitcnt lgkmcnt(2)
	v_pk_add_f32 v[74:75], v[74:75], v[114:115]
	v_pk_add_f32 v[78:79], v[78:79], v[112:113]
	s_waitcnt lgkmcnt(1)
	v_pk_add_f32 v[74:75], v[74:75], v[118:119]
	v_pk_add_f32 v[78:79], v[78:79], v[116:117]
	s_waitcnt lgkmcnt(0)
	v_pk_add_f32 v[66:67], v[74:75], v[122:123]
	v_lshl_add_u64 v[74:75], s[14:15], 0, v[72:73]
	v_lshlrev_b64 v[74:75], 1, v[74:75]
	v_pk_add_f32 v[64:65], v[78:79], v[120:121]
	v_lshl_add_u64 v[78:79], s[8:9], 0, v[74:75]
	global_load_dwordx2 v[78:79], v[78:79], off
	s_waitcnt vmcnt(0)
	v_lshlrev_b32_e32 v80, 16, v78
	v_and_b32_e32 v81, 0xffff0000, v78
	v_lshlrev_b32_e32 v78, 16, v79
	v_and_b32_e32 v79, 0xffff0000, v79
	v_pk_mul_f32 v[64:65], v[64:65], v[80:81]
	v_pk_mul_f32 v[66:67], v[66:67], v[78:79]
	v_cvt_pk_bf16_f32 v64, v64, v65
	v_cvt_pk_bf16_f32 v65, v66, v67
	v_lshl_add_u64 v[66:67], s[2:3], 0, v[74:75]
	global_store_dwordx2 v[66:67], v[64:65], off
	s_branch .LBB0_576

; __device__ __forceinline__ float bflo(unsigned w) { return __uint_as_float(w << 16); }
; __device__ __forceinline__ float bfhi(unsigned w) { return __uint_as_float(w & 0xffff0000u); }
; __device__ __forceinline__ u32x2 pack4(const f32x4 v) { u32x2 w; w.x = cvt_pk_bf16(v.x, v.y); w.y = cvt_pk_bf16(v.z, v.w); return w; }
;     __device__ __forceinline__ void apply(int row, int tile, int g, f32x4 v, f32x4) const { *(u32x2*)(O + (size_t)row * D + 16 * tile + 4 * g) = pack4(v); }
; template <class SE> __device__ __forceinline__ void skinny_gemm(const Frame& F, const bf16* Am, const bf16* Bt, int ntiles, int K, const SE& E) {
;     ...
;         part[w * 64 + F.lane] = acc0; if (SE::DUAL) part[512 + w * 64 + F.lane] = acc1;
;         asm volatile("s_waitcnt lgkmcnt(0)" ::: "memory"); __builtin_amdgcn_s_barrier(); asm volatile("" ::: "memory");
;         if (w == 0) {
;             f32x4 t0 = part[F.lane], t1 = {0.f, 0.f, 0.f, 0.f}; if (SE::DUAL) t1 = part[512 + F.lane];
; #pragma unroll
;             for (int ww = 1; ww < 8; ++ww) { t0 += part[ww * 64 + F.lane]; if (SE::DUAL) t1 += part[512 + ww * 64 + F.lane]; }
;             E.apply(MF + j, tile, g, t0, t1);
;     __device__ __forceinline__ void apply(int row, int tile, int g, f32x4 v, f32x4) const {
;         const size_t off = (size_t)row * D + 16 * tile + 4 * g; const u32x2 gg = *(const u32x2*)(G + off);
;         f32x4 o = {bflo(gg.x) * v.x, bfhi(gg.x) * v.y, bflo(gg.y) * v.z, bfhi(gg.y) * v.w};
;         if (ADD) { const u32x2 t = *(const u32x2*)(T + off); o.x += bflo(t.x); o.y += bfhi(t.x); o.z += bflo(t.y); o.w += bfhi(t.y); }
;         *(u32x2*)(O + off) = pack4(o);
.LBB0_678:
	ds_write_b128 v76, v[64:67]
	s_waitcnt lgkmcnt(0)
	s_barrier
	s_and_b64 vcc, exec, s[4:5]
	s_cbranch_vccz .LBB0_641
	ds_read_b128 v[64:67], v151
	ds_read_b128 v[78:81], v151 offset:1024
	ds_read_b128 v[100:103], v151 offset:2048
	ds_read_b128 v[104:107], v151 offset:3072
	ds_read_b128 v[108:111], v151 offset:4096
	ds_read_b128 v[112:115], v151 offset:5120
	ds_read_b128 v[116:119], v151 offset:6144
	ds_read_b128 v[120:123], v151 offset:7168
	s_ashr_i32 s7, s6, 31
	s_waitcnt lgkmcnt(6)
	v_pk_add_f32 v[74:75], v[66:67], v[80:81]
	v_pk_add_f32 v[78:79], v[64:65], v[78:79]
	s_waitcnt lgkmcnt(5)
	v_pk_add_f32 v[74:75], v[74:75], v[102:103]
	v_pk_add_f32 v[78:79], v[78:79], v[100:101]
	s_waitcnt lgkmcnt(4)
	v_pk_add_f32 v[74:75], v[74:75], v[106:107]
	v_pk_add_f32 v[78:79], v[78:79], v[104:105]
	s_waitcnt lgkmcnt(3)
	v_pk_add_f32 v[74:75], v[74:75], v[110:111]
	v_pk_add_f32 v[78:79], v[78:79], v[108:109]
	s_waitcnt lgkmcnt(2)
	v_pk_add_f32 v[74:75], v[74:75], v[114:115]
	v_pk_add_f32 v[78:79], v[78:79], v[112:113]
	s_waitcnt lgkmcnt(1)
	v_pk_add_f32 v[74:75], v[74:75], v[118:119]
	v_pk_add_f32 v[78:79], v[78:79], v[116:117]
	s_waitcnt lgkmcnt(0)
	v_pk_add_f32 v[66:67], v[74:75], v[122:123]
	v_lshl_add_u64 v[74:75], s[6:7], 0, v[72:73]
	v_lshlrev_b64 v[74:75], 1, v[74:75]
	v_pk_add_f32 v[64:65], v[78:79], v[120:121]
	v_lshl_add_u64 v[78:79], s[8:9], 0, v[74:75]
	v_lshl_add_u64 v[80:81], s[2:3], 0, v[74:75]
	global_load_dwordx2 v[78:79], v[78:79], off
	s_nop 0
	global_load_dwordx2 v[80:81], v[80:81], off
	s_waitcnt vmcnt(1)
	v_lshlrev_b32_e32 v82, 16, v78
	v_and_b32_e32 v83, 0xffff0000, v78
	s_waitcnt vmcnt(0)
	v_lshlrev_b32_e32 v84, 16, v80
	v_and_b32_e32 v85, 0xffff0000, v80
	v_lshlrev_b32_e32 v78, 16, v79
	v_and_b32_e32 v79, 0xffff0000, v79
	v_lshlrev_b32_e32 v80, 16, v81
	v_and_b32_e32 v81, 0xffff0000, v81
	v_pk_fma_f32 v[64:65], v[64:65], v[82:83], v[84:85]
	v_pk_fma_f32 v[66:67], v[66:67], v[78:79], v[80:81]
	v_cvt_pk_bf16_f32 v64, v64, v65
	v_cvt_pk_bf16_f32 v65, v66, v67
	v_lshl_add_u64 v[66:67], s[10:11], 0, v[74:75]
	global_store_dwordx2 v[66:67], v[64:65], off
	s_branch .LBB0_641

; __device__ __forceinline__ u32x2 pack4(const f32x4 v) { u32x2 w; w.x = cvt_pk_bf16(v.x, v.y); w.y = cvt_pk_bf16(v.z, v.w); return w; }
; template <class SE> __device__ __forceinline__ void skinny_gemm(const Frame& F, const bf16* Am, const bf16* Bt, int ntiles, int K, const SE& E) {
;     ...
;         part[w * 64 + F.lane] = acc0; if (SE::DUAL) part[512 + w * 64 + F.lane] = acc1;
;         asm volatile("s_waitcnt lgkmcnt(0)" ::: "memory"); __builtin_amdgcn_s_barrier(); asm volatile("" ::: "memory");
;         if (w == 0) {
;             f32x4 t0 = part[F.lane], t1 = {0.f, 0.f, 0.f, 0.f}; if (SE::DUAL) t1 = part[512 + F.lane];
; #pragma unroll
;             for (int ww = 1; ww < 8; ++ww) { t0 += part[ww * 64 + F.lane]; if (SE::DUAL) t1 += part[512 + ww * 64 + F.lane]; }
;             E.apply(MF + j, tile, g, t0, t1);
;     __device__ __forceinline__ void apply(int row, int tile, int g, f32x4 v, f32x4) const { *(u32x2*)(O + (size_t)row * D + 16 * tile + 4 * g) = pack4(v); }
.LBB0_795:
	ds_write_b128 v77, v[64:67]
	s_waitcnt lgkmcnt(0)
	s_barrier
	s_and_b64 vcc, exec, s[2:3]
	s_cbranch_vccz .LBB0_758
	ds_read_b128 v[64:67], v78
	ds_read_b128 v[80:83], v78 offset:1024
	ds_read_b128 v[100:103], v78 offset:2048
	ds_read_b128 v[104:107], v78 offset:3072
	ds_read_b128 v[108:111], v78 offset:4096
	ds_read_b128 v[112:115], v78 offset:5120
	ds_read_b128 v[116:119], v78 offset:6144
	ds_read_b128 v[120:123], v78 offset:7168
	s_ashr_i32 s5, s4, 31
	s_waitcnt lgkmcnt(6)
	v_pk_add_f32 v[74:75], v[66:67], v[82:83]
	v_pk_add_f32 v[80:81], v[64:65], v[80:81]
	s_waitcnt lgkmcnt(5)
	v_pk_add_f32 v[74:75], v[74:75], v[102:103]
	v_pk_add_f32 v[80:81], v[80:81], v[100:101]
	s_waitcnt lgkmcnt(4)
	v_pk_add_f32 v[74:75], v[74:75], v[106:107]
	v_pk_add_f32 v[80:81], v[80:81], v[104:105]
	s_waitcnt lgkmcnt(3)
	v_pk_add_f32 v[74:75], v[74:75], v[110:111]
	v_pk_add_f32 v[80:81], v[80:81], v[108:109]
	s_waitcnt lgkmcnt(2)
	v_pk_add_f32 v[74:75], v[74:75], v[114:115]
	v_pk_add_f32 v[80:81], v[80:81], v[112:113]
	s_waitcnt lgkmcnt(1)
	v_pk_add_f32 v[74:75], v[74:75], v[118:119]
	v_pk_add_f32 v[80:81], v[80:81], v[116:117]
	s_waitcnt lgkmcnt(0)
	v_pk_add_f32 v[66:67], v[74:75], v[122:123]
	v_pk_add_f32 v[64:65], v[80:81], v[120:121]
	s_nop 0
	v_cvt_pk_bf16_f32 v64, v64, v65
	v_cvt_pk_bf16_f32 v65, v66, v67
	v_lshl_add_u64 v[66:67], s[4:5], 1, v[72:73]
	global_store_dwordx2 v[66:67], v[64:65], off
	s_branch .LBB0_758

; __device__ __forceinline__ u32x2 pack4(const f32x4 v) { u32x2 w; w.x = cvt_pk_bf16(v.x, v.y); w.y = cvt_pk_bf16(v.z, v.w); return w; }
; template <class SE> __device__ __forceinline__ void skinny_gemm(const Frame& F, const bf16* Am, const bf16* Bt, int ntiles, int K, const SE& E) {
;     ...
;         part[w * 64 + F.lane] = acc0; if (SE::DUAL) part[512 + w * 64 + F.lane] = acc1;
;         asm volatile("s_waitcnt lgkmcnt(0)" ::: "memory"); __builtin_amdgcn_s_barrier(); asm volatile("" ::: "memory");
;         if (w == 0) {
;             f32x4 t0 = part[F.lane], t1 = {0.f, 0.f, 0.f, 0.f}; if (SE::DUAL) t1 = part[512 + F.lane];
; #pragma unroll
;             for (int ww = 1; ww < 8; ++ww) { t0 += part[ww * 64 + F.lane]; if (SE::DUAL) t1 += part[512 + ww * 64 + F.lane]; }
;             E.apply(MF + j, tile, g, t0, t1);
;     __device__ __forceinline__ void apply(int row, int tile, int g, f32x4 v, f32x4) const { *(u32x2*)(O + (size_t)row * D + 16 * tile + 4 * g) = pack4(v); }
.LBB0_1146:
	ds_write_b128 v77, v[64:67]
	s_waitcnt lgkmcnt(0)
	s_barrier
	s_and_b64 vcc, exec, s[2:3]
	s_cbranch_vccz .LBB0_1109
	ds_read_b128 v[64:67], v78
	ds_read_b128 v[80:83], v78 offset:1024
	ds_read_b128 v[100:103], v78 offset:2048
	ds_read_b128 v[104:107], v78 offset:3072
	ds_read_b128 v[108:111], v78 offset:4096
	ds_read_b128 v[112:115], v78 offset:5120
	ds_read_b128 v[116:119], v78 offset:6144
	ds_read_b128 v[120:123], v78 offset:7168
	s_ashr_i32 s7, s6, 31
	s_waitcnt lgkmcnt(6)
	v_pk_add_f32 v[74:75], v[66:67], v[82:83]
	v_pk_add_f32 v[80:81], v[64:65], v[80:81]
	s_waitcnt lgkmcnt(5)
	v_pk_add_f32 v[74:75], v[74:75], v[102:103]
	v_pk_add_f32 v[80:81], v[80:81], v[100:101]
	s_waitcnt lgkmcnt(4)
	v_pk_add_f32 v[74:75], v[74:75], v[106:107]
	v_pk_add_f32 v[80:81], v[80:81], v[104:105]
	s_waitcnt lgkmcnt(3)
	v_pk_add_f32 v[74:75], v[74:75], v[110:111]
	v_pk_add_f32 v[80:81], v[80:81], v[108:109]
	s_waitcnt lgkmcnt(2)
	v_pk_add_f32 v[74:75], v[74:75], v[114:115]
	v_pk_add_f32 v[80:81], v[80:81], v[112:113]
	s_waitcnt lgkmcnt(1)
	v_pk_add_f32 v[74:75], v[74:75], v[118:119]
	v_pk_add_f32 v[80:81], v[80:81], v[116:117]
	s_waitcnt lgkmcnt(0)
	v_pk_add_f32 v[66:67], v[74:75], v[122:123]
	v_pk_add_f32 v[64:65], v[80:81], v[120:121]
	s_nop 0
	v_cvt_pk_bf16_f32 v64, v64, v65
	v_cvt_pk_bf16_f32 v65, v66, v67
	v_lshl_add_u64 v[66:67], s[6:7], 1, v[72:73]
	global_store_dwordx2 v[66:67], v[64:65], off
	s_branch .LBB0_1109
